# XCD-local phase seams (G1->G2, G2->N2, G4->N3, N3->G5, G5->G6) with run-time XCC mapping guard, on top of v19
# baseline (speedup 1.0000x reference)
_Z8mega_fwd4Args:
	s_load_dwordx8 s[4:11], s[0:1], 0x80
	s_load_dword s3, s[0:1], 0xc0
	s_load_dwordx4 s[92:95], s[0:1], 0xa0
	s_load_dwordx2 s[50:51], s[0:1], 0xb8
	v_and_b32_e32 v226, 0x3ff, v0
	v_cmp_gt_u32_e32 vcc, 2, v226
	v_readfirstlane_b32 s33, v226
	s_waitcnt lgkmcnt(0)
	v_writelane_b32 v252, s4, 0
	s_nop 1
	v_writelane_b32 v252, s5, 1
	v_writelane_b32 v252, s6, 2
	v_writelane_b32 v252, s7, 3
	v_writelane_b32 v252, s8, 4
	v_writelane_b32 v252, s9, 5
	v_writelane_b32 v252, s10, 6
	v_writelane_b32 v252, s11, 7
	s_add_u32 s10, s0, 0xb8
	s_addc_u32 s11, s1, 0
	s_and_saveexec_b64 s[4:5], vcc
	v_lshl_add_u32 v1, v226, 2, 0
	v_add_u32_e32 v1, 0x23fe0, v1
	v_mov_b32_e32 v2, 0
	ds_write_b32 v1, v2
	s_or_b64 exec, exec, s[4:5]
	s_mov_b64 s[22:23], s[94:95]
	s_waitcnt lgkmcnt(0)
	s_barrier
	s_add_u32 s25, s22, 0x1000
	s_getreg_b32 s4, hwreg(HW_REG_XCC_ID, 0, 4)
	s_addc_u32 s27, s23, 0
	s_and_b32 s29, s4, 15
	v_cmp_eq_u32_e64 s[6:7], 0, v226
	s_mov_b64 s[4:5], exec
	s_nop 0
	v_writelane_b32 v252, s6, 8
	s_nop 1
	v_writelane_b32 v252, s7, 9
	s_and_b64 s[6:7], s[4:5], s[6:7]
	s_mov_b64 exec, s[6:7]
	s_cbranch_execz .LBB0_4
	s_lshl_b32 s6, s29, 8
	s_add_u32 s6, s25, s6
	s_addc_u32 s7, s27, 0
	v_mov_b32_e32 v1, 1
	v_mov_b64_e32 v[2:3], s[6:7]
	flat_atomic_add v[2:3], v1 offset:1024
	s_and_b32 s6, s2, 7
	s_cmp_eq_u32 s6, s29
	s_cbranch_scc1 .Lxcc_ok
	v_mov_b64_e32 v[4:5], s[22:23]
	flat_atomic_add v[4:5], v1 offset:3072
.Lxcc_ok:
.LBB0_4:
	s_or_b64 exec, exec, s[4:5]
	v_mov_b32_e32 v10, v226
	s_movk_i32 s4, 0x1000
	s_nop 0
	v_cmp_gt_i32_e32 vcc, s4, v10
	s_and_saveexec_b64 s[12:13], vcc
	s_cbranch_execz .LBB0_16
	v_max_i32_e32 v1, 0xe00, v10
	v_sub_u32_e32 v1, v1, v10
	s_movk_i32 s4, 0x1ff
	v_add_u32_e32 v2, 0x1ff, v1
	v_cmp_lt_u32_e32 vcc, s4, v2
	s_mov_b64 s[4:5], -1
	v_mov_b32_e32 v1, v10
	s_and_saveexec_b64 s[14:15], vcc
	s_cbranch_execz .LBB0_13
	v_lshrrev_b32_e32 v1, 9, v2
	v_add_u32_e32 v11, 0x200, v10
	v_add_u32_e32 v8, -1, v1
	v_cmp_lt_u32_e32 vcc, 1, v8
	v_mov_b32_e32 v4, 0
	v_mov_b64_e32 v[2:3], v[10:11]
	s_and_saveexec_b64 s[16:17], vcc
	s_cbranch_execz .LBB0_10
	v_lshrrev_b32_e32 v2, 1, v8
	s_mov_b32 s4, 0xbf1f24be
	v_add_u32_e32 v2, 1, v2
	v_mov_b64_e32 v[4:5], s[4:5]
	s_mov_b32 s4, 0x3e642e9d
	v_and_b32_e32 v9, -2, v2
	s_mov_b32 s21, 0
	v_lshl_add_u32 v12, v10, 2, 0
	s_mov_b64 s[18:19], 0
	s_mov_b32 s20, 0x3a000000
	s_mov_b32 s31, 0x7f800000
	s_mov_b32 s24, 0x3e75aa41
	s_mov_b32 s26, 0x40234736
	s_mov_b32 s28, 0xc0a55e0e
	s_mov_b32 s30, 0x40490fdb
	s_mov_b32 s34, 0x3d4be544
	v_mov_b64_e32 v[6:7], s[4:5]
	s_mov_b32 s36, 0xbfaad1da
	s_mov_b32 s38, 0x4081e0d3
	s_mov_b32 s40, 0xc09de9e6
	v_mov_b32_e32 v13, 0x1f8
	v_mov_b32_e32 v14, 0x7fc00000
	v_mov_b64_e32 v[2:3], v[10:11]

.LBB0_263:
	s_andn2_saveexec_b64 s[34:35], s[34:35]
	s_cbranch_execz .LBB0_279
	v_mov_b32_e32 v2, 0
	global_load_dword v2, v2, s[94:95] offset:3072 sc1
	s_waitcnt vmcnt(0)
	v_readfirstlane_b32 s8, v2
	s_cmp_eq_u32 s8, 0
	s_cbranch_scc1 .Lxbl_g1
	v_readlane_b32 s8, v253, 30
	v_readlane_b32 s9, v253, 31
	buffer_wbl2 sc1
	s_waitcnt vmcnt(0)
	s_mov_b64 s[36:37], -1
	v_mov_b64_e32 v[2:3], s[8:9]
	flat_atomic_add v1, v[2:3], v230 sc0
	v_cvt_f32_u32_e32 v2, v0
	v_sub_u32_e32 v3, 0, v0
	v_readlane_b32 s8, v253, 32
	v_readlane_b32 s9, v253, 33
	v_rcp_iflag_f32_e32 v2, v2
	s_nop 0
	v_mul_f32_e32 v2, 0x4f7ffffe, v2
	v_cvt_u32_f32_e32 v2, v2
	v_mul_lo_u32 v3, v3, v2
	v_mul_hi_u32 v3, v2, v3
	v_add_u32_e32 v2, v2, v3
	s_waitcnt vmcnt(0) lgkmcnt(0)
	v_mul_hi_u32 v2, v1, v2
	v_mul_lo_u32 v3, v2, v0
	v_sub_u32_e32 v3, v1, v3
	v_cmp_ge_u32_e32 vcc, v3, v0
	v_add_u32_e32 v4, 1, v2
	s_nop 0
	v_cndmask_b32_e32 v2, v2, v4, vcc
	v_sub_u32_e32 v4, v3, v0
	v_cndmask_b32_e32 v3, v3, v4, vcc
	v_cmp_ge_u32_e32 vcc, v3, v0
	v_add_u32_e32 v3, 1, v2
	s_nop 0
	v_cndmask_b32_e32 v2, v2, v3, vcc
	v_add_u32_e32 v3, 1, v1
	v_mad_u64_u32 v[0:1], s[34:35], v0, v2, v[0:1]
	v_cmp_ne_u32_e32 vcc, v3, v0
	v_mov_b64_e32 v[0:1], s[8:9]
	s_and_saveexec_b64 s[34:35], vcc
	s_cbranch_execz .LBB0_276
	v_readlane_b32 s8, v253, 32
	v_readlane_b32 s9, v253, 33
	s_mov_b64 s[38:39], 0
	s_nop 0
	v_mov_b64_e32 v[0:1], s[8:9]
	flat_load_dword v0, v[0:1] sc1
	s_waitcnt vmcnt(0) lgkmcnt(0)
	v_cmp_eq_u32_e32 vcc, v0, v2
	s_and_saveexec_b64 s[36:37], vcc
	s_cbranch_execz .LBB0_275
	s_mov_b32 s3, 1
	s_branch .LBB0_268

.Lxbl_g1:
	v_readlane_b32 s8, v253, 28
	v_readlane_b32 s9, v253, 29
	s_waitcnt vmcnt(0) lgkmcnt(0)
	buffer_inv sc1
	v_mov_b64_e32 v[0:1], s[8:9]
	flat_atomic_add v[0:1], v230
	s_waitcnt vmcnt(0)
